# v33 plus: two extra early L2 write-backs per XCD and barrier (workgroups arriving 12th and 5th from last)
# baseline (speedup 1.0000x reference)
; __device__ __forceinline__ unsigned xb_ld(unsigned* p)              { return __hip_atomic_load(p, __ATOMIC_RELAXED, __HIP_MEMORY_SCOPE_AGENT); }
; __device__ __forceinline__ unsigned xb_add(unsigned* p, unsigned v) { return __hip_atomic_fetch_add(p, v, __ATOMIC_RELAXED, __HIP_MEMORY_SCOPE_AGENT); }
; #define XB_SPIN(cond, bar) do { unsigned _sp = 0; while (cond) { __builtin_amdgcn_s_sleep(1); \
;     if ((++_sp & 255u) == 0u) { if (xb_ld(&(bar)[XB_TMO])) break; if (_sp > XB_SPIN_CAP) { atomicAdd(&(bar)[XB_TMO], 1u); break; } } } } while (0)
; __device__ __forceinline__ void xcd_barrier(const XcdBarrier& b) {
;     ...
;         const unsigned old = xb_add(&bar[XB_XSUB(b.x)], 1u);
;         const unsigned gen = old / nloc;
;         if (old + 1u == (gen + 1u) * nloc) {
;             __builtin_amdgcn_fence(__ATOMIC_RELEASE, "agent");
;             asm volatile("s_waitcnt vmcnt(0)" ::: "memory");
;             const unsigned og = xb_add(&bar[XB_TOP], 1u);
;             const unsigned tg = og / nx;
;             if (og + 1u == (tg + 1u) * nx) xb_add(&bar[XB_TOPGEN], 1u);
;             else XB_SPIN(xb_ld(&bar[XB_TOPGEN]) == tg, bar);
;             __builtin_amdgcn_fence(__ATOMIC_ACQUIRE, "agent");
;             xb_add(&bar[XB_XGEN(b.x)], 1u);
;             asm volatile("s_waitcnt vmcnt(0)" ::: "memory");
;         } else {
;             XB_SPIN(xb_ld(&bar[XB_XGEN(b.x)]) == gen, bar);
.LBB0_117:
	s_or_b64 exec, exec, s[14:15]
	buffer_inv sc1
	v_cvt_f32_u32_e32 v4, v2
	s_waitcnt vmcnt(1)
	v_readfirstlane_b32 s12, v3
	v_sub_u32_e32 v3, 0, v2
	v_rcp_iflag_f32_e32 v4, v4
	v_add_u32_e32 v5, s12, v1
	v_mul_f32_e32 v4, 0x4f7ffffe, v4
	v_cvt_u32_f32_e32 v4, v4
	v_mul_lo_u32 v1, v3, v4
	v_mul_hi_u32 v1, v4, v1
	v_add_u32_e32 v1, v4, v1
	v_mul_hi_u32 v1, v5, v1
	v_mul_lo_u32 v3, v1, v2
	v_sub_u32_e32 v3, v5, v3
	v_add_u32_e32 v4, 1, v1
	v_cmp_ge_u32_e32 vcc, v3, v2
	s_nop 1
	v_cndmask_b32_e32 v1, v1, v4, vcc
	v_sub_u32_e32 v4, v3, v2
	v_cndmask_b32_e32 v3, v3, v4, vcc
	v_add_u32_e32 v4, 1, v1
	v_cmp_ge_u32_e32 vcc, v3, v2
	v_add_u32_e32 v3, 1, v5
	s_nop 0
	v_cndmask_b32_e32 v1, v1, v4, vcc
	v_mul_lo_u32 v4, v2, v1
	v_add_u32_e32 v2, v4, v2
	v_cmp_ne_u32_e32 vcc, v3, v2
	s_and_saveexec_b64 s[12:13], vcc
	s_xor_b64 s[12:13], exec, s[12:13]
	s_cbranch_execz .LBB0_131
	v_sub_u32_e32 v251, v2, v3
	v_cmp_eq_u32_e32 vcc, 12, v251
	s_cbranch_vccnz .Lbar_early_0
	v_cmp_eq_u32_e32 vcc, 5, v251
	s_cbranch_vccz .Lbar_noearly_0
.Lbar_early_0:
	buffer_wbl2 sc1

; __device__ __forceinline__ unsigned xb_ld(unsigned* p)              { return __hip_atomic_load(p, __ATOMIC_RELAXED, __HIP_MEMORY_SCOPE_AGENT); }
; __device__ __forceinline__ unsigned xb_add(unsigned* p, unsigned v) { return __hip_atomic_fetch_add(p, v, __ATOMIC_RELAXED, __HIP_MEMORY_SCOPE_AGENT); }
; #define XB_SPIN(cond, bar) do { unsigned _sp = 0; while (cond) { __builtin_amdgcn_s_sleep(1); \
;     if ((++_sp & 255u) == 0u) { if (xb_ld(&(bar)[XB_TMO])) break; if (_sp > XB_SPIN_CAP) { atomicAdd(&(bar)[XB_TMO], 1u); break; } } } } while (0)
; __device__ __forceinline__ void xcd_barrier(const XcdBarrier& b) {
;     ...
;         const unsigned old = xb_add(&bar[XB_XSUB(b.x)], 1u);
;         const unsigned gen = old / nloc;
;         if (old + 1u == (gen + 1u) * nloc) {
;             __builtin_amdgcn_fence(__ATOMIC_RELEASE, "agent");
;             asm volatile("s_waitcnt vmcnt(0)" ::: "memory");
;             const unsigned og = xb_add(&bar[XB_TOP], 1u);
;             const unsigned tg = og / nx;
;             if (og + 1u == (tg + 1u) * nx) xb_add(&bar[XB_TOPGEN], 1u);
;             else XB_SPIN(xb_ld(&bar[XB_TOPGEN]) == tg, bar);
;             __builtin_amdgcn_fence(__ATOMIC_ACQUIRE, "agent");
;             xb_add(&bar[XB_XGEN(b.x)], 1u);
;             asm volatile("s_waitcnt vmcnt(0)" ::: "memory");
;         } else {
;             XB_SPIN(xb_ld(&bar[XB_XGEN(b.x)]) == gen, bar);
.LBB0_328:
	s_or_b64 exec, exec, s[12:13]
	buffer_inv sc1
	v_cvt_f32_u32_e32 v4, v2
	s_waitcnt vmcnt(1)
	v_readfirstlane_b32 s10, v3
	v_sub_u32_e32 v3, 0, v2
	v_rcp_iflag_f32_e32 v4, v4
	v_add_u32_e32 v5, s10, v1
	v_mul_f32_e32 v4, 0x4f7ffffe, v4
	v_cvt_u32_f32_e32 v4, v4
	v_mul_lo_u32 v1, v3, v4
	v_mul_hi_u32 v1, v4, v1
	v_add_u32_e32 v1, v4, v1
	v_mul_hi_u32 v1, v5, v1
	v_mul_lo_u32 v3, v1, v2
	v_sub_u32_e32 v3, v5, v3
	v_add_u32_e32 v4, 1, v1
	v_cmp_ge_u32_e32 vcc, v3, v2
	s_nop 1
	v_cndmask_b32_e32 v1, v1, v4, vcc
	v_sub_u32_e32 v4, v3, v2
	v_cndmask_b32_e32 v3, v3, v4, vcc
	v_add_u32_e32 v4, 1, v1
	v_cmp_ge_u32_e32 vcc, v3, v2
	v_add_u32_e32 v3, 1, v5
	s_nop 0
	v_cndmask_b32_e32 v1, v1, v4, vcc
	v_mul_lo_u32 v4, v2, v1
	v_add_u32_e32 v2, v4, v2
	v_cmp_ne_u32_e32 vcc, v3, v2
	s_and_saveexec_b64 s[10:11], vcc
	s_xor_b64 s[10:11], exec, s[10:11]
	s_cbranch_execz .LBB0_342
	v_sub_u32_e32 v251, v2, v3
	v_cmp_eq_u32_e32 vcc, 12, v251
	s_cbranch_vccnz .Lbar_early_1
	v_cmp_eq_u32_e32 vcc, 5, v251
	s_cbranch_vccz .Lbar_noearly_1

; __device__ __forceinline__ unsigned xb_ld(unsigned* p)              { return __hip_atomic_load(p, __ATOMIC_RELAXED, __HIP_MEMORY_SCOPE_AGENT); }
; __device__ __forceinline__ unsigned xb_add(unsigned* p, unsigned v) { return __hip_atomic_fetch_add(p, v, __ATOMIC_RELAXED, __HIP_MEMORY_SCOPE_AGENT); }
; #define XB_SPIN(cond, bar) do { unsigned _sp = 0; while (cond) { __builtin_amdgcn_s_sleep(1); \
;     if ((++_sp & 255u) == 0u) { if (xb_ld(&(bar)[XB_TMO])) break; if (_sp > XB_SPIN_CAP) { atomicAdd(&(bar)[XB_TMO], 1u); break; } } } } while (0)
; __device__ __forceinline__ void xcd_barrier(const XcdBarrier& b) {
;     ...
;         const unsigned old = xb_add(&bar[XB_XSUB(b.x)], 1u);
;         const unsigned gen = old / nloc;
;         if (old + 1u == (gen + 1u) * nloc) {
;             __builtin_amdgcn_fence(__ATOMIC_RELEASE, "agent");
;             asm volatile("s_waitcnt vmcnt(0)" ::: "memory");
;             const unsigned og = xb_add(&bar[XB_TOP], 1u);
;             const unsigned tg = og / nx;
;             if (og + 1u == (tg + 1u) * nx) xb_add(&bar[XB_TOPGEN], 1u);
;             else XB_SPIN(xb_ld(&bar[XB_TOPGEN]) == tg, bar);
;             __builtin_amdgcn_fence(__ATOMIC_ACQUIRE, "agent");
;             xb_add(&bar[XB_XGEN(b.x)], 1u);
;             asm volatile("s_waitcnt vmcnt(0)" ::: "memory");
;         } else {
;             XB_SPIN(xb_ld(&bar[XB_XGEN(b.x)]) == gen, bar);
.LBB0_419:
	s_or_b64 exec, exec, s[22:23]
	buffer_inv sc1
	v_cvt_f32_u32_e32 v4, v2
	s_waitcnt vmcnt(1)
	v_readfirstlane_b32 s11, v3
	v_sub_u32_e32 v3, 0, v2
	v_rcp_iflag_f32_e32 v4, v4
	v_add_u32_e32 v5, s11, v1
	v_mul_f32_e32 v4, 0x4f7ffffe, v4
	v_cvt_u32_f32_e32 v4, v4
	v_mul_lo_u32 v1, v3, v4
	v_mul_hi_u32 v1, v4, v1
	v_add_u32_e32 v1, v4, v1
	v_mul_hi_u32 v1, v5, v1
	v_mul_lo_u32 v3, v1, v2
	v_sub_u32_e32 v3, v5, v3
	v_add_u32_e32 v4, 1, v1
	v_cmp_ge_u32_e32 vcc, v3, v2
	s_nop 1
	v_cndmask_b32_e32 v1, v1, v4, vcc
	v_sub_u32_e32 v4, v3, v2
	v_cndmask_b32_e32 v3, v3, v4, vcc
	v_add_u32_e32 v4, 1, v1
	v_cmp_ge_u32_e32 vcc, v3, v2
	v_add_u32_e32 v3, 1, v5
	s_nop 0
	v_cndmask_b32_e32 v1, v1, v4, vcc
	v_mul_lo_u32 v4, v2, v1
	v_add_u32_e32 v2, v4, v2
	v_cmp_ne_u32_e32 vcc, v3, v2
	s_and_saveexec_b64 s[12:13], vcc
	s_xor_b64 s[22:23], exec, s[12:13]
	s_cbranch_execz .LBB0_433
	v_sub_u32_e32 v251, v2, v3
	v_cmp_eq_u32_e32 vcc, 12, v251
	s_cbranch_vccnz .Lbar_early_2
	v_cmp_eq_u32_e32 vcc, 5, v251
	s_cbranch_vccz .Lbar_noearly_2

; __device__ __forceinline__ unsigned xb_ld(unsigned* p)              { return __hip_atomic_load(p, __ATOMIC_RELAXED, __HIP_MEMORY_SCOPE_AGENT); }
; __device__ __forceinline__ unsigned xb_add(unsigned* p, unsigned v) { return __hip_atomic_fetch_add(p, v, __ATOMIC_RELAXED, __HIP_MEMORY_SCOPE_AGENT); }
; #define XB_SPIN(cond, bar) do { unsigned _sp = 0; while (cond) { __builtin_amdgcn_s_sleep(1); \
;     if ((++_sp & 255u) == 0u) { if (xb_ld(&(bar)[XB_TMO])) break; if (_sp > XB_SPIN_CAP) { atomicAdd(&(bar)[XB_TMO], 1u); break; } } } } while (0)
; __device__ __forceinline__ void xcd_barrier(const XcdBarrier& b) {
;     ...
;         const unsigned old = xb_add(&bar[XB_XSUB(b.x)], 1u);
;         const unsigned gen = old / nloc;
;         if (old + 1u == (gen + 1u) * nloc) {
;             __builtin_amdgcn_fence(__ATOMIC_RELEASE, "agent");
;             asm volatile("s_waitcnt vmcnt(0)" ::: "memory");
;             const unsigned og = xb_add(&bar[XB_TOP], 1u);
;             const unsigned tg = og / nx;
;             if (og + 1u == (tg + 1u) * nx) xb_add(&bar[XB_TOPGEN], 1u);
;             else XB_SPIN(xb_ld(&bar[XB_TOPGEN]) == tg, bar);
;             __builtin_amdgcn_fence(__ATOMIC_ACQUIRE, "agent");
;             xb_add(&bar[XB_XGEN(b.x)], 1u);
;             asm volatile("s_waitcnt vmcnt(0)" ::: "memory");
;         } else {
;             XB_SPIN(xb_ld(&bar[XB_XGEN(b.x)]) == gen, bar);
.LBB0_1389:
	s_or_b64 exec, exec, s[22:23]
	buffer_inv sc1
	v_cvt_f32_u32_e32 v4, v2
	s_waitcnt vmcnt(1)
	v_readfirstlane_b32 s6, v3
	v_sub_u32_e32 v3, 0, v2
	v_rcp_iflag_f32_e32 v4, v4
	v_add_u32_e32 v5, s6, v1
	v_mul_f32_e32 v4, 0x4f7ffffe, v4
	v_cvt_u32_f32_e32 v4, v4
	v_mul_lo_u32 v1, v3, v4
	v_mul_hi_u32 v1, v4, v1
	v_add_u32_e32 v1, v4, v1
	v_mul_hi_u32 v1, v5, v1
	v_mul_lo_u32 v3, v1, v2
	v_sub_u32_e32 v3, v5, v3
	v_add_u32_e32 v4, 1, v1
	v_cmp_ge_u32_e32 vcc, v3, v2
	s_nop 1
	v_cndmask_b32_e32 v1, v1, v4, vcc
	v_sub_u32_e32 v4, v3, v2
	v_cndmask_b32_e32 v3, v3, v4, vcc
	v_add_u32_e32 v4, 1, v1
	v_cmp_ge_u32_e32 vcc, v3, v2
	v_add_u32_e32 v3, 1, v5
	s_nop 0
	v_cndmask_b32_e32 v1, v1, v4, vcc
	v_mul_lo_u32 v4, v2, v1
	v_add_u32_e32 v2, v4, v2
	v_cmp_ne_u32_e32 vcc, v3, v2
	s_and_saveexec_b64 s[16:17], vcc
	s_xor_b64 s[22:23], exec, s[16:17]
	s_cbranch_execz .LBB0_1403
	v_sub_u32_e32 v251, v2, v3
	v_cmp_eq_u32_e32 vcc, 12, v251
	s_cbranch_vccnz .Lbar_early_8
	v_cmp_eq_u32_e32 vcc, 5, v251
	s_cbranch_vccz .Lbar_noearly_8

; __device__ __forceinline__ unsigned xb_ld(unsigned* p)              { return __hip_atomic_load(p, __ATOMIC_RELAXED, __HIP_MEMORY_SCOPE_AGENT); }
; __device__ __forceinline__ unsigned xb_add(unsigned* p, unsigned v) { return __hip_atomic_fetch_add(p, v, __ATOMIC_RELAXED, __HIP_MEMORY_SCOPE_AGENT); }
; #define XB_SPIN(cond, bar) do { unsigned _sp = 0; while (cond) { __builtin_amdgcn_s_sleep(1); \
;     if ((++_sp & 255u) == 0u) { if (xb_ld(&(bar)[XB_TMO])) break; if (_sp > XB_SPIN_CAP) { atomicAdd(&(bar)[XB_TMO], 1u); break; } } } } while (0)
; __device__ __forceinline__ void xcd_barrier(const XcdBarrier& b) {
;     ...
;         const unsigned old = xb_add(&bar[XB_XSUB(b.x)], 1u);
;         const unsigned gen = old / nloc;
;         if (old + 1u == (gen + 1u) * nloc) {
;             __builtin_amdgcn_fence(__ATOMIC_RELEASE, "agent");
;             asm volatile("s_waitcnt vmcnt(0)" ::: "memory");
;             const unsigned og = xb_add(&bar[XB_TOP], 1u);
;             const unsigned tg = og / nx;
;             if (og + 1u == (tg + 1u) * nx) xb_add(&bar[XB_TOPGEN], 1u);
;             else XB_SPIN(xb_ld(&bar[XB_TOPGEN]) == tg, bar);
;             __builtin_amdgcn_fence(__ATOMIC_ACQUIRE, "agent");
;             xb_add(&bar[XB_XGEN(b.x)], 1u);
;             asm volatile("s_waitcnt vmcnt(0)" ::: "memory");
;         } else {
;             XB_SPIN(xb_ld(&bar[XB_XGEN(b.x)]) == gen, bar);
.LBB0_2162:
	s_or_b64 exec, exec, s[22:23]
	buffer_inv sc1
	v_cvt_f32_u32_e32 v4, v2
	s_waitcnt vmcnt(1)
	v_readfirstlane_b32 s6, v3
	v_sub_u32_e32 v3, 0, v2
	v_rcp_iflag_f32_e32 v4, v4
	v_add_u32_e32 v5, s6, v1
	v_mul_f32_e32 v4, 0x4f7ffffe, v4
	v_cvt_u32_f32_e32 v4, v4
	v_mul_lo_u32 v1, v3, v4
	v_mul_hi_u32 v1, v4, v1
	v_add_u32_e32 v1, v4, v1
	v_mul_hi_u32 v1, v5, v1
	v_mul_lo_u32 v3, v1, v2
	v_sub_u32_e32 v3, v5, v3
	v_add_u32_e32 v4, 1, v1
	v_cmp_ge_u32_e32 vcc, v3, v2
	s_nop 1
	v_cndmask_b32_e32 v1, v1, v4, vcc
	v_sub_u32_e32 v4, v3, v2
	v_cndmask_b32_e32 v3, v3, v4, vcc
	v_add_u32_e32 v4, 1, v1
	v_cmp_ge_u32_e32 vcc, v3, v2
	v_add_u32_e32 v3, 1, v5
	s_nop 0
	v_cndmask_b32_e32 v1, v1, v4, vcc
	v_mul_lo_u32 v4, v2, v1
	v_add_u32_e32 v2, v4, v2
	v_cmp_ne_u32_e32 vcc, v3, v2
	s_and_saveexec_b64 s[14:15], vcc
	s_xor_b64 s[22:23], exec, s[14:15]
	s_cbranch_execz .LBB0_2176
	v_sub_u32_e32 v251, v2, v3
	v_cmp_eq_u32_e32 vcc, 12, v251
	s_cbranch_vccnz .Lbar_early_14
	v_cmp_eq_u32_e32 vcc, 5, v251
	s_cbranch_vccz .Lbar_noearly_14

; __device__ __forceinline__ unsigned xb_ld(unsigned* p)              { return __hip_atomic_load(p, __ATOMIC_RELAXED, __HIP_MEMORY_SCOPE_AGENT); }
; __device__ __forceinline__ unsigned xb_add(unsigned* p, unsigned v) { return __hip_atomic_fetch_add(p, v, __ATOMIC_RELAXED, __HIP_MEMORY_SCOPE_AGENT); }
; #define XB_SPIN(cond, bar) do { unsigned _sp = 0; while (cond) { __builtin_amdgcn_s_sleep(1); \
;     if ((++_sp & 255u) == 0u) { if (xb_ld(&(bar)[XB_TMO])) break; if (_sp > XB_SPIN_CAP) { atomicAdd(&(bar)[XB_TMO], 1u); break; } } } } while (0)
; __device__ __forceinline__ void xcd_barrier(const XcdBarrier& b) {
;     ...
;         const unsigned old = xb_add(&bar[XB_XSUB(b.x)], 1u);
;         const unsigned gen = old / nloc;
;         if (old + 1u == (gen + 1u) * nloc) {
;             __builtin_amdgcn_fence(__ATOMIC_RELEASE, "agent");
;             asm volatile("s_waitcnt vmcnt(0)" ::: "memory");
;             const unsigned og = xb_add(&bar[XB_TOP], 1u);
;             const unsigned tg = og / nx;
;             if (og + 1u == (tg + 1u) * nx) xb_add(&bar[XB_TOPGEN], 1u);
;             else XB_SPIN(xb_ld(&bar[XB_TOPGEN]) == tg, bar);
;             __builtin_amdgcn_fence(__ATOMIC_ACQUIRE, "agent");
;             xb_add(&bar[XB_XGEN(b.x)], 1u);
;             asm volatile("s_waitcnt vmcnt(0)" ::: "memory");
;         } else {
;             XB_SPIN(xb_ld(&bar[XB_XGEN(b.x)]) == gen, bar);
.LBB0_2258:
	s_or_b64 exec, exec, s[22:23]
	buffer_inv sc1
	v_cvt_f32_u32_e32 v4, v2
	s_waitcnt vmcnt(1)
	v_readfirstlane_b32 s11, v3
	v_sub_u32_e32 v3, 0, v2
	v_rcp_iflag_f32_e32 v4, v4
	v_add_u32_e32 v5, s11, v1
	v_mul_f32_e32 v4, 0x4f7ffffe, v4
	v_cvt_u32_f32_e32 v4, v4
	v_mul_lo_u32 v1, v3, v4
	v_mul_hi_u32 v1, v4, v1
	v_add_u32_e32 v1, v4, v1
	v_mul_hi_u32 v1, v5, v1
	v_mul_lo_u32 v3, v1, v2
	v_sub_u32_e32 v3, v5, v3
	v_add_u32_e32 v4, 1, v1
	v_cmp_ge_u32_e32 vcc, v3, v2
	s_nop 1
	v_cndmask_b32_e32 v1, v1, v4, vcc
	v_sub_u32_e32 v4, v3, v2
	v_cndmask_b32_e32 v3, v3, v4, vcc
	v_add_u32_e32 v4, 1, v1
	v_cmp_ge_u32_e32 vcc, v3, v2
	v_add_u32_e32 v3, 1, v5
	s_nop 0
	v_cndmask_b32_e32 v1, v1, v4, vcc
	v_mul_lo_u32 v4, v2, v1
	v_add_u32_e32 v2, v4, v2
	v_cmp_ne_u32_e32 vcc, v3, v2
	s_and_saveexec_b64 s[14:15], vcc
	s_xor_b64 s[22:23], exec, s[14:15]
	s_cbranch_execz .LBB0_2272
	v_sub_u32_e32 v251, v2, v3
	v_cmp_eq_u32_e32 vcc, 12, v251
	s_cbranch_vccnz .Lbar_early_15
	v_cmp_eq_u32_e32 vcc, 5, v251
	s_cbranch_vccz .Lbar_noearly_15

; __device__ __forceinline__ unsigned xb_ld(unsigned* p)              { return __hip_atomic_load(p, __ATOMIC_RELAXED, __HIP_MEMORY_SCOPE_AGENT); }
; __device__ __forceinline__ unsigned xb_add(unsigned* p, unsigned v) { return __hip_atomic_fetch_add(p, v, __ATOMIC_RELAXED, __HIP_MEMORY_SCOPE_AGENT); }
; #define XB_SPIN(cond, bar) do { unsigned _sp = 0; while (cond) { __builtin_amdgcn_s_sleep(1); \
;     if ((++_sp & 255u) == 0u) { if (xb_ld(&(bar)[XB_TMO])) break; if (_sp > XB_SPIN_CAP) { atomicAdd(&(bar)[XB_TMO], 1u); break; } } } } while (0)
; __device__ __forceinline__ void xcd_barrier(const XcdBarrier& b) {
;     ...
;         const unsigned old = xb_add(&bar[XB_XSUB(b.x)], 1u);
;         const unsigned gen = old / nloc;
;         if (old + 1u == (gen + 1u) * nloc) {
;             __builtin_amdgcn_fence(__ATOMIC_RELEASE, "agent");
;             asm volatile("s_waitcnt vmcnt(0)" ::: "memory");
;             const unsigned og = xb_add(&bar[XB_TOP], 1u);
;             const unsigned tg = og / nx;
;             if (og + 1u == (tg + 1u) * nx) xb_add(&bar[XB_TOPGEN], 1u);
;             else XB_SPIN(xb_ld(&bar[XB_TOPGEN]) == tg, bar);
;             __builtin_amdgcn_fence(__ATOMIC_ACQUIRE, "agent");
;             xb_add(&bar[XB_XGEN(b.x)], 1u);
;             asm volatile("s_waitcnt vmcnt(0)" ::: "memory");
;         } else {
;             XB_SPIN(xb_ld(&bar[XB_XGEN(b.x)]) == gen, bar);
.LBB0_2618:
	s_or_b64 exec, exec, s[2:3]
	buffer_inv sc1
	v_cvt_f32_u32_e32 v4, v2
	s_waitcnt vmcnt(1)
	v_readfirstlane_b32 s2, v3
	v_sub_u32_e32 v3, 0, v2
	v_rcp_iflag_f32_e32 v4, v4
	v_add_u32_e32 v5, s2, v1
	v_mul_f32_e32 v4, 0x4f7ffffe, v4
	v_cvt_u32_f32_e32 v4, v4
	v_mul_lo_u32 v1, v3, v4
	v_mul_hi_u32 v1, v4, v1
	v_add_u32_e32 v1, v4, v1
	v_mul_hi_u32 v1, v5, v1
	v_mul_lo_u32 v3, v1, v2
	v_sub_u32_e32 v3, v5, v3
	v_add_u32_e32 v4, 1, v1
	v_cmp_ge_u32_e32 vcc, v3, v2
	s_nop 1
	v_cndmask_b32_e32 v1, v1, v4, vcc
	v_sub_u32_e32 v4, v3, v2
	v_cndmask_b32_e32 v3, v3, v4, vcc
	v_add_u32_e32 v4, 1, v1
	v_cmp_ge_u32_e32 vcc, v3, v2
	v_add_u32_e32 v3, 1, v5
	s_nop 0
	v_cndmask_b32_e32 v1, v1, v4, vcc
	v_mul_lo_u32 v4, v2, v1
	v_add_u32_e32 v2, v4, v2
	v_cmp_ne_u32_e32 vcc, v3, v2
	s_and_saveexec_b64 s[2:3], vcc
	s_xor_b64 s[2:3], exec, s[2:3]
	s_cbranch_execz .LBB0_2632
	v_sub_u32_e32 v251, v2, v3
	v_cmp_eq_u32_e32 vcc, 12, v251
	s_cbranch_vccnz .Lbar_early_17
	v_cmp_eq_u32_e32 vcc, 5, v251
	s_cbranch_vccz .Lbar_noearly_17
